# P0 row loop: b_forget bias loaded once before the loop (was reloaded per row behind the hn stores with vmcnt(0)); loop-top wait is vmcnt(5) so rows no longer wait for store acks
# speedup vs baseline: 1.0062x; 1.0062x over previous
.LBB0_110:
	v_lshlrev_b32_e32 v80, 12, v223
	s_add_i32 s0, 0, 0x18000
	v_and_b32_e32 v80, 0x7000, v80
	v_add_u32_e32 v80, s0, v80
	s_waitcnt vmcnt(14)
	v_mul_f32_e32 v64, v137, v172
	v_lshl_add_u32 v81, v135, 2, v80
	v_mul_f32_e32 v65, v139, v140
	ds_write_b32 v81, v64
	v_lshl_add_u32 v64, v136, 2, v80
	s_waitcnt vmcnt(13)
	v_mul_f32_e32 v66, v142, v171
	v_mul_f32_e32 v67, v143, v144
	ds_write_b32 v64, v65
	ds_write_b32 v81, v66 offset:512
	v_lshl_add_u32 v64, v138, 2, v80
	s_waitcnt vmcnt(12)
	v_mul_f32_e32 v68, v146, v170
	v_mul_f32_e32 v69, v147, v148
	ds_write_b32 v64, v67
	ds_write_b32 v81, v68 offset:1024
	v_lshl_add_u32 v64, v141, 2, v80
	s_waitcnt vmcnt(11)
	v_mul_f32_e32 v70, v150, v169
	v_mul_f32_e32 v71, v151, v152
	ds_write_b32 v64, v69
	ds_write_b32 v81, v70 offset:1536
	v_lshl_add_u32 v64, v145, 2, v80
	s_waitcnt vmcnt(10)
	v_mul_f32_e32 v72, v154, v167
	v_mul_f32_e32 v73, v155, v156
	ds_write_b32 v64, v71
	ds_write_b32 v81, v72 offset:2048
	v_lshl_add_u32 v64, v149, 2, v80
	s_waitcnt vmcnt(9)
	v_mul_f32_e32 v74, v158, v166
	v_mul_f32_e32 v75, v159, v160
	ds_write_b32 v64, v73
	ds_write_b32 v81, v74 offset:2560
	v_lshl_add_u32 v64, v153, 2, v80
	s_waitcnt vmcnt(8)
	v_mul_f32_e32 v76, v162, v165
	v_mul_f32_e32 v77, v163, v164
	ds_write_b32 v64, v75
	ds_write_b32 v81, v76 offset:3072
	v_lshl_add_u32 v64, v157, 2, v80
	s_waitcnt vmcnt(6)
	v_mul_f32_e32 v78, v173, v168
	s_waitcnt vmcnt(4)
	v_mul_f32_e32 v79, v174, v175
	ds_write_b32 v64, v77
	ds_write_b32 v81, v78 offset:3584
	v_lshl_add_u32 v64, v161, 2, v80
	s_and_b64 vcc, exec, s[10:11]
	v_lshlrev_b32_e32 v210, 3, v224
	ds_write_b32 v64, v79
	s_waitcnt lgkmcnt(0)
	s_barrier
	s_cbranch_vccz .LBB0_117
	v_mbcnt_lo_u32_b32 v64, -1, 0
	v_mbcnt_hi_u32_b32 v64, -1, v64
	v_and_b32_e32 v65, 64, v64
	v_add_u32_e32 v65, 64, v65
	v_xor_b32_e32 v66, 1, v64
	v_cmp_lt_i32_e32 vcc, v66, v65
	v_mov_b32_e32 v209, 0
	v_readlane_b32 s8, v252, 8
	v_cndmask_b32_e32 v66, v64, v66, vcc
	v_lshlrev_b32_e32 v225, 2, v66
	v_xor_b32_e32 v66, 2, v64
	v_cmp_lt_i32_e32 vcc, v66, v65
	v_readlane_b32 s16, v252, 16
	v_readlane_b32 s17, v252, 17
	v_cndmask_b32_e32 v66, v64, v66, vcc
	v_lshlrev_b32_e32 v226, 2, v66
	v_xor_b32_e32 v66, 4, v64
	v_cmp_lt_i32_e32 vcc, v66, v65
	s_mov_b64 s[0:1], 0x2700000
	v_readlane_b32 s9, v252, 9
	v_cndmask_b32_e32 v66, v64, v66, vcc
	v_lshlrev_b32_e32 v227, 2, v66
	v_xor_b32_e32 v66, 8, v64
	v_cmp_lt_i32_e32 vcc, v66, v65
	v_readlane_b32 s10, v252, 10
	v_readlane_b32 s11, v252, 11
	v_cndmask_b32_e32 v66, v64, v66, vcc
	v_lshlrev_b32_e32 v228, 2, v66
	v_xor_b32_e32 v66, 16, v64
	v_cmp_lt_i32_e32 vcc, v66, v65
	v_readlane_b32 s12, v252, 12
	v_readlane_b32 s13, v252, 13
	v_cndmask_b32_e32 v66, v64, v66, vcc
	v_lshlrev_b32_e32 v229, 2, v66
	v_xor_b32_e32 v66, 32, v64
	v_cmp_lt_i32_e32 vcc, v66, v65
	v_mov_b32_e32 v65, v209
	v_readlane_b32 s14, v252, 14
	v_cndmask_b32_e32 v64, v64, v66, vcc
	v_lshlrev_b32_e32 v230, 2, v64
	v_add_u32_e32 v64, 0, v208
	v_add_u32_e32 v188, 0x18000, v64
	v_lshlrev_b32_e32 v64, 2, v224
	v_lshl_add_u64 v[216:217], s[16:17], 0, v[64:65]
	v_and_b32_e32 v226, 28, v64
	v_mov_b32_e32 v227, 0
	v_lshl_add_u64 v[226:227], s[16:17], 0, v[226:227]
	global_load_dword v225, v[226:227], off
	v_lshl_add_u64 v[64:65], s[30:31], 0, v[64:65]
	v_lshl_add_u64 v[218:219], v[64:65], 0, s[0:1]
	ds_read_b128 v[64:67], v188
	ds_read_b128 v[68:71], v188 offset:1024
	ds_read_b128 v[72:75], v188 offset:2048
	ds_read_b128 v[76:79], v188 offset:3072
	ds_read_b128 v[80:83], v188 offset:4096
	ds_read_b128 v[84:87], v188 offset:5120
	ds_read_b128 v[88:91], v188 offset:6144
	ds_read_b128 v[92:95], v188 offset:7168
	ds_read_b128 v[96:99], v188 offset:8192
	ds_read_b128 v[100:103], v188 offset:9216
	ds_read_b128 v[104:107], v188 offset:10240
	ds_read_b128 v[108:111], v188 offset:11264
	ds_read_b128 v[112:115], v188 offset:12288
	ds_read_b128 v[116:119], v188 offset:13312
	ds_read_b128 v[120:123], v188 offset:14336
	ds_read_b128 v[124:127], v188 offset:15360
	ds_read_b128 v[128:131], v188 offset:16384
	ds_read_b128 v[132:135], v188 offset:17408
	ds_read_b128 v[136:139], v188 offset:18432
	ds_read_b128 v[140:143], v188 offset:19456
	ds_read_b128 v[144:147], v188 offset:20480
	ds_read_b128 v[148:151], v188 offset:21504
	ds_read_b128 v[152:155], v188 offset:22528
	ds_read_b128 v[156:159], v188 offset:23552
	ds_read_b128 v[160:163], v188 offset:24576
	ds_read_b128 v[164:167], v188 offset:25600
	ds_read_b128 v[168:171], v188 offset:26624
	ds_read_b128 v[172:175], v188 offset:27648
	ds_read_b128 v[176:179], v188 offset:28672
	ds_read_b128 v[180:183], v188 offset:29696
	ds_read_b128 v[184:187], v188 offset:30720
	ds_read_b128 v[188:191], v188 offset:31744
	v_readlane_b32 s15, v252, 15
	v_readlane_b32 s18, v252, 18
	v_readlane_b32 s19, v252, 19
	v_readlane_b32 s20, v252, 20
	v_readlane_b32 s21, v252, 21
	v_readlane_b32 s22, v252, 22
	v_readlane_b32 s23, v252, 23
	v_mov_b32_e32 v211, v209
	s_lshl_b32 s3, s26, 4
	v_lshl_add_u64 v[212:213], s[8:9], 0, v[208:209]
	v_lshl_add_u64 v[214:215], s[24:25], 0, v[210:211]
	v_cmp_gt_u32_e32 vcc, 8, v224
	v_cmp_eq_u32_e64 s[8:9], 0, v224
	v_cmp_eq_u32_e64 s[10:11], 1, v224
	v_cmp_eq_u32_e64 s[12:13], 2, v224
	v_cmp_eq_u32_e64 s[14:15], 3, v224
	v_cmp_eq_u32_e64 s[16:17], 4, v224
	v_cmp_eq_u32_e64 s[18:19], 5, v224
	v_cmp_eq_u32_e64 s[20:21], 6, v224
	v_cmp_eq_u32_e64 s[22:23], 7, v224
	v_mov_b32_e32 v209, 0x358637bd
	s_mov_b32 s27, 0x800000
	s_mov_b32 s35, 0xbfb8aa3b
	s_mov_b32 s41, 0x3f2aaaab
	v_mov_b32_e32 v211, 0x3ecc95a3
	s_mov_b32 s52, 0x3f317218
	s_mov_b32 s53, 0x7f800000
	s_mov_b32 s54, 0x33800000
	v_mov_b32_e32 v220, 0x3f317218
	v_mov_b32_e32 v231, 0x7f800000
	v_mov_b32_e32 v232, 0x7fc00000
	v_mov_b32_e32 v233, 0xff800000
	s_mov_b32 s68, s86
	s_waitcnt vmcnt(0)
	s_branch .LBB0_113
.LBB0_112:
	s_or_b64 exec, exec, s[70:71]
	s_sub_i32 s68, s44, s84
	v_mov_b64_e32 v[60:61], v[204:205]
	v_mov_b64_e32 v[56:57], v[200:201]
	v_mov_b64_e32 v[52:53], v[196:197]
	v_mov_b64_e32 v[48:49], v[192:193]
	s_cmpk_gt_i32 s68, 0x3fff
	v_mov_b64_e32 v[62:63], v[206:207]
	v_mov_b64_e32 v[58:59], v[202:203]
	v_mov_b64_e32 v[54:55], v[198:199]
	v_mov_b64_e32 v[50:51], v[194:195]
	s_cbranch_scc1 .LBB0_117
	s_waitcnt vmcnt(5)
.LBB0_113:
	v_mov_b64_e32 v[194:195], v[46:47]
	v_mov_b64_e32 v[198:199], v[42:43]
	v_mov_b64_e32 v[202:203], v[38:39]
	s_add_i32 s44, s68, s3
	v_mov_b64_e32 v[206:207], v[34:35]
	v_mov_b64_e32 v[192:193], v[44:45]
	v_mov_b64_e32 v[196:197], v[40:41]
	v_mov_b64_e32 v[200:201], v[36:37]
	s_cmpk_lt_i32 s44, 0x4000
	v_mov_b64_e32 v[204:205], v[32:33]
	s_cbranch_scc0 .LBB0_115
	s_ashr_i32 s45, s44, 31
	s_lshl_b64 s[0:1], s[44:45], 12
	v_lshl_add_u64 v[44:45], v[212:213], 0, s[0:1]
	global_load_dwordx4 v[32:35], v[44:45], off nt
	global_load_dwordx4 v[36:39], v[44:45], off offset:1024 nt
	global_load_dwordx4 v[40:43], v[44:45], off offset:2048 nt
	s_nop 0
	global_load_dwordx4 v[44:47], v[44:45], off offset:3072 nt
.LBB0_115:
	v_mul_f32_e32 v221, v61, v61
	v_mul_f32_e32 v222, v63, v63
	v_fmac_f32_e32 v221, v60, v60
	v_fmac_f32_e32 v222, v62, v62
	v_add_f32_e32 v221, v221, v222
	v_mul_f32_e32 v222, v57, v57
	s_waitcnt lgkmcnt(7)
	v_mul_f32_e32 v234, v59, v59
	v_fmac_f32_e32 v222, v56, v56
	v_fmac_f32_e32 v234, v58, v58
	v_add_f32_e32 v222, v222, v234
	v_add_f32_e32 v221, v221, v222
	v_mul_f32_e32 v222, v53, v53
	v_mul_f32_e32 v234, v55, v55
	v_fmac_f32_e32 v222, v52, v52
	v_fmac_f32_e32 v234, v54, v54
	v_add_f32_e32 v222, v222, v234
	v_add_f32_e32 v221, v221, v222
	v_mul_f32_e32 v222, v49, v49
	v_mul_f32_e32 v234, v51, v51
	v_fmac_f32_e32 v222, v48, v48
	v_fmac_f32_e32 v234, v50, v50
	v_add_f32_e32 v222, v222, v234
	v_add_f32_e32 v221, v221, v222
	s_nop 1
	v_mov_b32_dpp v222, v221 quad_perm:[1,0,3,2] row_mask:0xf bank_mask:0xf
	s_waitcnt lgkmcnt(7)
	v_mul_f32_e32 v234, v61, v65
	v_mul_f32_e32 v235, v63, v67
	v_fmac_f32_e32 v234, v60, v64
	v_fmac_f32_e32 v235, v62, v66
	s_waitcnt lgkmcnt(0)
	v_add_f32_e32 v221, v221, v222
	s_nop 1
	v_mov_b32_dpp v222, v221 quad_perm:[2,3,0,1] row_mask:0xf bank_mask:0xf
	v_add_f32_e32 v234, v234, v235
	v_mul_f32_e32 v235, v57, v69
	v_mul_f32_e32 v236, v59, v71
	v_fmac_f32_e32 v235, v56, v68
	s_waitcnt lgkmcnt(0)
	v_add_f32_e32 v221, v221, v222
	s_nop 1
	v_mov_b32_dpp v222, v221 row_half_mirror row_mask:0xf bank_mask:0xf
	v_fmac_f32_e32 v236, v58, v70
	v_add_f32_e32 v234, 0, v234
	v_add_f32_e32 v235, v235, v236
	v_add_f32_e32 v234, v234, v235
	s_waitcnt lgkmcnt(0)
	v_add_f32_e32 v221, v221, v222
	v_mul_f32_e32 v235, v53, v73
	v_mul_f32_e32 v236, v55, v75
	v_mov_b32_dpp v222, v221 row_mirror row_mask:0xf bank_mask:0xf
	v_fmac_f32_e32 v235, v52, v72
	v_fmac_f32_e32 v236, v54, v74
	v_add_f32_e32 v235, v235, v236
	v_add_f32_e32 v234, v234, v235
	v_mul_f32_e32 v235, v49, v77
	v_mul_f32_e32 v236, v51, v79
	v_fmac_f32_e32 v235, v48, v76
	v_fmac_f32_e32 v236, v50, v78
	v_add_f32_e32 v235, v235, v236
	s_waitcnt lgkmcnt(0)
	v_add_f32_e32 v221, v221, v222
	v_add_f32_e32 v234, v234, v235
	v_mul_f32_e32 v236, v61, v81
	v_mul_f32_e32 v237, v63, v83
	v_mov_b32_e32 v222, v221
	s_nop 1
	v_permlane16_swap_b32_e32 v222, v221
	v_mov_b32_dpp v235, v234 quad_perm:[1,0,3,2] row_mask:0xf bank_mask:0xf
	v_fmac_f32_e32 v236, v60, v80
	v_fmac_f32_e32 v237, v62, v82
	v_add_f32_e32 v236, v236, v237
	v_mul_f32_e32 v237, v57, v85
	v_mul_f32_e32 v238, v59, v87
	v_fmac_f32_e32 v237, v56, v84
	v_fmac_f32_e32 v238, v58, v86
	v_add_f32_e32 v236, 0, v236
	v_add_f32_e32 v237, v237, v238
	v_add_f32_e32 v236, v236, v237
	v_mul_f32_e32 v237, v53, v89
	v_mul_f32_e32 v238, v55, v91
	v_fmac_f32_e32 v237, v52, v88
	v_fmac_f32_e32 v238, v54, v90
	s_waitcnt lgkmcnt(0)
	v_add_f32_e32 v221, v221, v222
	s_waitcnt lgkmcnt(0)
	v_add_f32_e32 v234, v234, v235
	v_add_f32_e32 v237, v237, v238
	v_mov_b32_e32 v222, v221
	s_nop 1
	v_permlane32_swap_b32_e32 v222, v221
	v_mov_b32_dpp v235, v234 quad_perm:[2,3,0,1] row_mask:0xf bank_mask:0xf
	v_add_f32_e32 v236, v236, v237
	v_mul_f32_e32 v237, v49, v93
	v_mul_f32_e32 v238, v51, v95
	v_fmac_f32_e32 v237, v48, v92
	v_fmac_f32_e32 v238, v50, v94
	v_add_f32_e32 v237, v237, v238
	v_add_f32_e32 v236, v236, v237
	s_nop 1
	v_mov_b32_dpp v237, v236 quad_perm:[1,0,3,2] row_mask:0xf bank_mask:0xf
	s_waitcnt lgkmcnt(0)
	v_add_f32_e32 v221, v221, v222
	s_waitcnt lgkmcnt(0)
	v_add_f32_e32 v222, v234, v235
	s_nop 1
	v_mov_b32_dpp v234, v222 row_half_mirror row_mask:0xf bank_mask:0xf
	v_fmamk_f32 v221, v221, 0x3a800000, v209
	s_waitcnt lgkmcnt(0)
	v_add_f32_e32 v236, v236, v237
	s_nop 1
	v_mov_b32_dpp v237, v236 quad_perm:[2,3,0,1] row_mask:0xf bank_mask:0xf
	v_cmp_gt_f32_e64 s[0:1], s27, v221
	s_waitcnt lgkmcnt(0)
	v_add_f32_e32 v222, v222, v234
	s_nop 1
	v_mov_b32_dpp v234, v222 row_mirror row_mask:0xf bank_mask:0xf
	v_mul_f32_e32 v238, v63, v99
	s_waitcnt lgkmcnt(0)
	v_add_f32_e32 v235, v236, v237
	v_mul_f32_e32 v237, 0x4b800000, v221
	v_cndmask_b32_e64 v221, v221, v237, s[0:1]
	s_waitcnt lgkmcnt(0)
	v_add_f32_e32 v234, v222, v234
	v_rsq_f32_e32 v221, v221
	v_mov_b32_e32 v237, v234
	s_nop 1
	v_permlane16_swap_b32_e32 v237, v234
	v_fmac_f32_e32 v238, v62, v98
	v_mul_f32_e32 v239, v59, v103
	v_mul_f32_e32 v222, 0x45800000, v221
	v_cndmask_b32_e64 v222, v221, v222, s[0:1]
	s_waitcnt lgkmcnt(0)
	v_add_f32_e32 v221, v234, v237
	v_mul_f32_e32 v237, v61, v97
	v_fmac_f32_e32 v237, v60, v96
	v_add_f32_e32 v237, v237, v238
	v_mul_f32_e32 v238, v57, v101
	v_fmac_f32_e32 v238, v56, v100
	v_fmac_f32_e32 v239, v58, v102
	v_add_f32_e32 v237, 0, v237
	v_add_f32_e32 v238, v238, v239
	v_add_f32_e32 v237, v237, v238
	v_mul_f32_e32 v238, v53, v105
	v_mul_f32_e32 v239, v55, v107
	v_fmac_f32_e32 v238, v52, v104
	v_fmac_f32_e32 v239, v54, v106
	v_add_f32_e32 v238, v238, v239
	v_add_f32_e32 v237, v237, v238
	v_mul_f32_e32 v238, v49, v109
	v_mul_f32_e32 v239, v51, v111
	v_fmac_f32_e32 v238, v48, v108
	v_fmac_f32_e32 v239, v50, v110
	v_add_f32_e32 v238, v238, v239
	v_mul_f32_e32 v239, v61, v113
	v_mul_f32_e32 v240, v63, v115
	v_fmac_f32_e32 v239, v60, v112
	v_fmac_f32_e32 v240, v62, v114
	v_add_f32_e32 v239, v239, v240
	v_mul_f32_e32 v240, v57, v117
	v_mul_f32_e32 v241, v59, v119
	v_fmac_f32_e32 v240, v56, v116
	v_fmac_f32_e32 v241, v58, v118
	v_add_f32_e32 v239, 0, v239
	v_add_f32_e32 v240, v240, v241
	v_add_f32_e32 v239, v239, v240
	v_mul_f32_e32 v240, v53, v121
	v_mul_f32_e32 v241, v55, v123
	v_fmac_f32_e32 v240, v52, v120
	v_fmac_f32_e32 v241, v54, v122
	v_add_f32_e32 v240, v240, v241
	v_add_f32_e32 v239, v239, v240
	v_mul_f32_e32 v240, v49, v125
	v_mul_f32_e32 v241, v51, v127
	v_fmac_f32_e32 v240, v48, v124
	v_fmac_f32_e32 v241, v50, v126
	v_add_f32_e32 v240, v240, v241
	v_mul_f32_e32 v241, v61, v129
	v_mul_f32_e32 v242, v63, v131
	v_fmac_f32_e32 v241, v60, v128
	v_fmac_f32_e32 v242, v62, v130
	v_add_f32_e32 v241, v241, v242
	v_mul_f32_e32 v242, v57, v133
	v_mul_f32_e32 v243, v59, v135
	v_fmac_f32_e32 v242, v56, v132
	v_fmac_f32_e32 v243, v58, v134
	v_add_f32_e32 v241, 0, v241
	v_add_f32_e32 v242, v242, v243
	v_add_f32_e32 v241, v241, v242
	v_mul_f32_e32 v242, v53, v137
	v_mul_f32_e32 v243, v55, v139
	v_fmac_f32_e32 v242, v52, v136
	v_fmac_f32_e32 v243, v54, v138
	v_add_f32_e32 v242, v242, v243
	v_add_f32_e32 v241, v241, v242
	v_mul_f32_e32 v242, v49, v141
	v_mul_f32_e32 v243, v51, v143
	v_fmac_f32_e32 v242, v48, v140
	v_fmac_f32_e32 v243, v50, v142
	v_add_f32_e32 v242, v242, v243
	v_mul_f32_e32 v243, v61, v145
	v_mul_f32_e32 v244, v63, v147
	v_fmac_f32_e32 v243, v60, v144
	v_fmac_f32_e32 v244, v62, v146
	v_add_f32_e32 v243, v243, v244
	v_mul_f32_e32 v244, v57, v149
	v_mul_f32_e32 v245, v59, v151
	v_fmac_f32_e32 v244, v56, v148
	v_fmac_f32_e32 v245, v58, v150
	v_add_f32_e32 v243, 0, v243
	v_add_f32_e32 v244, v244, v245
	v_add_f32_e32 v243, v243, v244
	v_mul_f32_e32 v244, v53, v153
	v_mul_f32_e32 v245, v55, v155
	v_fmac_f32_e32 v244, v52, v152
	v_fmac_f32_e32 v245, v54, v154
	v_add_f32_e32 v244, v244, v245
	v_add_f32_e32 v243, v243, v244
	v_mul_f32_e32 v244, v49, v157
	v_mul_f32_e32 v245, v51, v159
	v_fmac_f32_e32 v244, v48, v156
	v_fmac_f32_e32 v245, v50, v158
	v_add_f32_e32 v244, v244, v245
	v_mul_f32_e32 v245, v61, v161
	v_mul_f32_e32 v246, v63, v163
	v_fmac_f32_e32 v245, v60, v160
	v_fmac_f32_e32 v246, v62, v162
	v_add_f32_e32 v245, v245, v246
	v_mul_f32_e32 v246, v57, v165
	v_mul_f32_e32 v247, v59, v167
	v_fmac_f32_e32 v246, v56, v164
	v_fmac_f32_e32 v247, v58, v166
	v_add_f32_e32 v245, 0, v245
	v_add_f32_e32 v246, v246, v247
	v_add_f32_e32 v245, v245, v246
	v_mul_f32_e32 v246, v53, v169
	v_mul_f32_e32 v247, v55, v171
	v_fmac_f32_e32 v246, v52, v168
	v_fmac_f32_e32 v247, v54, v170
	v_add_f32_e32 v246, v246, v247
	v_add_f32_e32 v245, v245, v246
	v_mul_f32_e32 v246, v49, v173
	v_mul_f32_e32 v247, v51, v175
	v_fmac_f32_e32 v246, v48, v172
	v_fmac_f32_e32 v247, v50, v174
	v_add_f32_e32 v246, v246, v247
	v_mul_f32_e32 v247, v61, v177
	v_mul_f32_e32 v248, v63, v179
	v_fmac_f32_e32 v247, v60, v176
	v_fmac_f32_e32 v248, v62, v178
	v_add_f32_e32 v247, v247, v248
	v_mul_f32_e32 v248, v57, v181
	v_mul_f32_e32 v249, v59, v183
	v_fmac_f32_e32 v248, v56, v180
	v_fmac_f32_e32 v249, v58, v182
	v_add_f32_e32 v247, 0, v247
	v_add_f32_e32 v248, v248, v249
	v_add_f32_e32 v247, v247, v248
	v_mul_f32_e32 v248, v53, v185
	v_mul_f32_e32 v249, v55, v187
	v_fmac_f32_e32 v248, v52, v184
	v_fmac_f32_e32 v249, v54, v186
	v_add_f32_e32 v248, v248, v249
	v_add_f32_e32 v247, v247, v248
	v_mul_f32_e32 v248, v49, v189
	v_mul_f32_e32 v249, v51, v191
	v_fmac_f32_e32 v248, v48, v188
	v_fmac_f32_e32 v249, v50, v190
	v_add_f32_e32 v248, v248, v249
	v_add_f32_e32 v237, v237, v238
	v_add_f32_e32 v239, v239, v240
	v_add_f32_e32 v241, v241, v242
	v_add_f32_e32 v243, v243, v244
	v_add_f32_e32 v245, v245, v246
	v_add_f32_e32 v247, v247, v248
	v_mov_b32_dpp v238, v237 quad_perm:[1,0,3,2] row_mask:0xf bank_mask:0xf
	v_mov_b32_dpp v240, v239 quad_perm:[1,0,3,2] row_mask:0xf bank_mask:0xf
	v_mov_b32_dpp v242, v241 quad_perm:[1,0,3,2] row_mask:0xf bank_mask:0xf
	v_mov_b32_dpp v244, v243 quad_perm:[1,0,3,2] row_mask:0xf bank_mask:0xf
	v_mov_b32_dpp v246, v245 quad_perm:[1,0,3,2] row_mask:0xf bank_mask:0xf
	v_mov_b32_dpp v248, v247 quad_perm:[1,0,3,2] row_mask:0xf bank_mask:0xf
	s_waitcnt lgkmcnt(0)
	v_add_f32_e32 v237, v237, v238
	s_waitcnt lgkmcnt(0)
	v_add_f32_e32 v239, v239, v240
	s_waitcnt lgkmcnt(0)
	v_add_f32_e32 v241, v241, v242
	s_waitcnt lgkmcnt(0)
	v_add_f32_e32 v243, v243, v244
	s_waitcnt lgkmcnt(0)
	v_add_f32_e32 v245, v245, v246
	s_waitcnt lgkmcnt(0)
	v_add_f32_e32 v247, v247, v248
	v_mov_b32_dpp v238, v237 quad_perm:[2,3,0,1] row_mask:0xf bank_mask:0xf
	v_mov_b32_dpp v240, v239 quad_perm:[2,3,0,1] row_mask:0xf bank_mask:0xf
	v_mov_b32_dpp v242, v241 quad_perm:[2,3,0,1] row_mask:0xf bank_mask:0xf
	v_mov_b32_dpp v244, v243 quad_perm:[2,3,0,1] row_mask:0xf bank_mask:0xf
	v_mov_b32_dpp v246, v245 quad_perm:[2,3,0,1] row_mask:0xf bank_mask:0xf
	v_mov_b32_dpp v248, v247 quad_perm:[2,3,0,1] row_mask:0xf bank_mask:0xf
	s_waitcnt lgkmcnt(0)
	v_add_f32_e32 v237, v237, v238
	s_waitcnt lgkmcnt(0)
	v_add_f32_e32 v239, v239, v240
	s_waitcnt lgkmcnt(0)
	v_add_f32_e32 v241, v241, v242
	s_waitcnt lgkmcnt(0)
	v_add_f32_e32 v243, v243, v244
	s_waitcnt lgkmcnt(0)
	v_add_f32_e32 v245, v245, v246
	s_waitcnt lgkmcnt(0)
	v_add_f32_e32 v247, v247, v248
	v_mov_b32_dpp v236, v235 row_half_mirror row_mask:0xf bank_mask:0xf
	v_mov_b32_dpp v238, v237 row_half_mirror row_mask:0xf bank_mask:0xf
	v_mov_b32_dpp v240, v239 row_half_mirror row_mask:0xf bank_mask:0xf
	v_mov_b32_dpp v242, v241 row_half_mirror row_mask:0xf bank_mask:0xf
	v_mov_b32_dpp v244, v243 row_half_mirror row_mask:0xf bank_mask:0xf
	v_mov_b32_dpp v246, v245 row_half_mirror row_mask:0xf bank_mask:0xf
	v_mov_b32_dpp v248, v247 row_half_mirror row_mask:0xf bank_mask:0xf
	s_waitcnt lgkmcnt(0)
	v_add_f32_e32 v235, v235, v236
	s_waitcnt lgkmcnt(0)
	v_add_f32_e32 v237, v237, v238
	s_waitcnt lgkmcnt(0)
	v_add_f32_e32 v239, v239, v240
	s_waitcnt lgkmcnt(0)
	v_add_f32_e32 v241, v241, v242
	s_waitcnt lgkmcnt(0)
	v_add_f32_e32 v243, v243, v244
	s_waitcnt lgkmcnt(0)
	v_add_f32_e32 v245, v245, v246
	s_waitcnt lgkmcnt(0)
	v_add_f32_e32 v247, v247, v248
	v_mov_b32_dpp v236, v235 row_mirror row_mask:0xf bank_mask:0xf
	v_mov_b32_dpp v238, v237 row_mirror row_mask:0xf bank_mask:0xf
	v_mov_b32_dpp v240, v239 row_mirror row_mask:0xf bank_mask:0xf
	v_mov_b32_dpp v242, v241 row_mirror row_mask:0xf bank_mask:0xf
	v_mov_b32_dpp v244, v243 row_mirror row_mask:0xf bank_mask:0xf
	v_mov_b32_dpp v246, v245 row_mirror row_mask:0xf bank_mask:0xf
	v_mov_b32_dpp v248, v247 row_mirror row_mask:0xf bank_mask:0xf
	s_waitcnt lgkmcnt(0)
	v_add_f32_e32 v235, v235, v236
	s_waitcnt lgkmcnt(0)
	v_add_f32_e32 v237, v237, v238
	s_waitcnt lgkmcnt(0)
	v_add_f32_e32 v239, v239, v240
	s_waitcnt lgkmcnt(0)
	v_add_f32_e32 v241, v241, v242
	s_waitcnt lgkmcnt(0)
	v_add_f32_e32 v243, v243, v244
	s_waitcnt lgkmcnt(0)
	v_add_f32_e32 v245, v245, v246
	s_waitcnt lgkmcnt(0)
	v_add_f32_e32 v247, v247, v248
	v_mov_b32_e32 v236, v235
	s_nop 1
	v_permlane16_swap_b32_e32 v236, v235
	v_mov_b32_e32 v238, v237
	s_nop 1
	v_permlane16_swap_b32_e32 v238, v237
	v_mov_b32_e32 v240, v239
	s_nop 1
	v_permlane16_swap_b32_e32 v240, v239
	v_mov_b32_e32 v242, v241
	s_nop 1
	v_permlane16_swap_b32_e32 v242, v241
	v_mov_b32_e32 v244, v243
	s_nop 1
	v_permlane16_swap_b32_e32 v244, v243
	v_mov_b32_e32 v246, v245
	s_nop 1
	v_permlane16_swap_b32_e32 v246, v245
	v_mov_b32_e32 v248, v247
	s_nop 1
	v_permlane16_swap_b32_e32 v248, v247
	s_waitcnt lgkmcnt(0)
	v_add_f32_e32 v235, v235, v236
	s_waitcnt lgkmcnt(0)
	v_add_f32_e32 v237, v237, v238
	s_waitcnt lgkmcnt(0)
	v_add_f32_e32 v239, v239, v240
	s_waitcnt lgkmcnt(0)
	v_add_f32_e32 v241, v241, v242
	s_waitcnt lgkmcnt(0)
	v_add_f32_e32 v243, v243, v244
	s_waitcnt lgkmcnt(0)
	v_add_f32_e32 v245, v245, v246
	s_waitcnt lgkmcnt(0)
	v_add_f32_e32 v247, v247, v248
	v_mov_b32_e32 v234, v221
	s_nop 1
	v_permlane32_swap_b32_e32 v234, v221
	v_mov_b32_e32 v236, v235
	s_nop 1
	v_permlane32_swap_b32_e32 v236, v235
	v_mov_b32_e32 v238, v237
	s_nop 1
	v_permlane32_swap_b32_e32 v238, v237
	v_mov_b32_e32 v240, v239
	s_nop 1
	v_permlane32_swap_b32_e32 v240, v239
	v_mov_b32_e32 v242, v241
	s_nop 1
	v_permlane32_swap_b32_e32 v242, v241
	v_mov_b32_e32 v244, v243
	s_nop 1
	v_permlane32_swap_b32_e32 v244, v243
	v_mov_b32_e32 v246, v245
	s_nop 1
	v_permlane32_swap_b32_e32 v246, v245
	v_mov_b32_e32 v248, v247
	s_nop 1
	v_permlane32_swap_b32_e32 v248, v247
	s_ashr_i32 s69, s68, 31
	v_pk_mul_f32 v[62:63], v[18:19], v[62:63]
	v_pk_mul_f32 v[60:61], v[16:17], v[60:61]
	v_pk_mul_f32 v[58:59], v[22:23], v[58:59]
	v_pk_mul_f32 v[56:57], v[20:21], v[56:57]
	v_pk_mul_f32 v[54:55], v[26:27], v[54:55]
	v_pk_mul_f32 v[52:53], v[24:25], v[52:53]
	v_pk_mul_f32 v[50:51], v[30:31], v[50:51]
	v_pk_mul_f32 v[48:49], v[28:29], v[48:49]
	s_lshl_b64 s[0:1], s[68:69], 11
	v_pk_mul_f32 v[62:63], v[62:63], v[222:223] op_sel_hi:[1,0]
	v_pk_mul_f32 v[60:61], v[60:61], v[222:223] op_sel_hi:[1,0]
	v_pk_mul_f32 v[58:59], v[58:59], v[222:223] op_sel_hi:[1,0]
	v_pk_mul_f32 v[56:57], v[56:57], v[222:223] op_sel_hi:[1,0]
	v_pk_mul_f32 v[54:55], v[54:55], v[222:223] op_sel_hi:[1,0]
	v_pk_mul_f32 v[52:53], v[52:53], v[222:223] op_sel_hi:[1,0]
	v_pk_mul_f32 v[50:51], v[50:51], v[222:223] op_sel_hi:[1,0]
	v_pk_mul_f32 v[48:49], v[48:49], v[222:223] op_sel_hi:[1,0]
	v_lshl_add_u64 v[250:251], v[214:215], 0, s[0:1]
	v_cvt_pk_bf16_f32 v60, v60, v61
	v_cvt_pk_bf16_f32 v61, v62, v63
	v_cvt_pk_bf16_f32 v56, v56, v57
	v_cvt_pk_bf16_f32 v57, v58, v59
	v_cvt_pk_bf16_f32 v52, v52, v53
	v_cvt_pk_bf16_f32 v53, v54, v55
	v_cvt_pk_bf16_f32 v48, v48, v49
	v_cvt_pk_bf16_f32 v49, v50, v51
	global_store_dwordx2 v[250:251], v[60:61], off
	global_store_dwordx2 v[250:251], v[56:57], off offset:512
	global_store_dwordx2 v[250:251], v[52:53], off offset:1024
	global_store_dwordx2 v[250:251], v[48:49], off offset:1536
	s_and_saveexec_b64 s[70:71], vcc
	s_cbranch_execz .LBB0_112
	s_waitcnt lgkmcnt(0)
	v_add_f32_e32 v56, v221, v234
	s_waitcnt lgkmcnt(0)
	v_add_f32_e32 v55, v235, v236
	v_mul_f32_e32 v56, v222, v56
	s_waitcnt lgkmcnt(0)
	v_add_f32_e32 v54, v237, v238
	v_mul_f32_e32 v55, v222, v55
	v_cndmask_b32_e64 v56, 0, v56, s[8:9]
	s_waitcnt lgkmcnt(0)
	v_add_f32_e32 v53, v239, v240
	v_mul_f32_e32 v54, v222, v54
	v_cndmask_b32_e64 v55, v56, v55, s[10:11]
	s_waitcnt lgkmcnt(0)
	v_add_f32_e32 v52, v241, v242
	v_mul_f32_e32 v53, v222, v53
	v_cndmask_b32_e64 v54, v55, v54, s[12:13]
	s_waitcnt lgkmcnt(0)
	v_add_f32_e32 v51, v243, v244
	v_mul_f32_e32 v52, v222, v52
	v_cndmask_b32_e64 v53, v54, v53, s[14:15]
	s_waitcnt lgkmcnt(0)
	v_add_f32_e32 v50, v245, v246
	v_mul_f32_e32 v51, v222, v51
	v_cndmask_b32_e64 v52, v53, v52, s[16:17]
	s_waitcnt lgkmcnt(0)
	v_add_f32_e32 v49, v247, v248
	v_mul_f32_e32 v50, v222, v50
	v_cndmask_b32_e64 v51, v52, v51, s[18:19]
	v_mul_f32_e32 v49, v222, v49
	v_cndmask_b32_e64 v50, v51, v50, s[20:21]
	v_cndmask_b32_e64 v49, v50, v49, s[22:23]
	s_lshl_b64 s[68:69], s[68:69], 5
	v_add_f32_e32 v48, v49, v225
	v_mul_f32_e64 v49, |v48|, s35
	v_exp_f32_e32 v62, v49
	v_min_f32_e32 v63, 0, v48
	v_add_f32_e32 v50, 1.0, v62
	v_add_f32_e32 v51, -1.0, v50
	v_frexp_mant_f32_e32 v52, v50
	v_cvt_f64_f32_e32 v[48:49], v50
	v_sub_f32_e32 v53, v51, v50
	v_frexp_exp_i32_f64_e32 v48, v[48:49]
	v_cmp_gt_f32_e64 s[0:1], s41, v52
	v_sub_f32_e32 v51, v62, v51
	v_add_f32_e32 v49, 1.0, v53
	v_subbrev_co_u32_e64 v48, s[0:1], 0, v48, s[0:1]
	v_add_f32_e32 v49, v51, v49
	v_sub_u32_e32 v51, 0, v48
	v_ldexp_f32 v50, v50, v51
	v_add_f32_e32 v52, -1.0, v50
	v_add_f32_e32 v53, 1.0, v50
	v_ldexp_f32 v49, v49, v51
	v_add_f32_e32 v51, 1.0, v52
	v_add_f32_e32 v54, -1.0, v53
	v_sub_f32_e32 v51, v50, v51
	v_sub_f32_e32 v50, v50, v54
	v_add_f32_e32 v54, v49, v51
	v_add_f32_e32 v49, v49, v50
	v_add_f32_e32 v56, v53, v49
	v_rcp_f32_e32 v57, v56
	v_add_f32_e32 v51, v52, v54
	v_sub_f32_e32 v52, v51, v52
	v_sub_f32_e32 v50, v56, v53
	v_mul_f32_e32 v59, v51, v57
	v_sub_f32_e32 v58, v54, v52
	v_mul_f32_e32 v52, v56, v59
	v_sub_f32_e32 v49, v49, v50
	v_fma_f32 v54, v59, v56, -v52
	v_fmac_f32_e32 v54, v59, v49
	v_add_f32_e32 v50, v52, v54
	v_sub_f32_e32 v53, v51, v50
	v_mov_b32_e32 v55, v50
	v_pk_add_f32 v[50:51], v[50:51], v[52:53] neg_lo:[0,1] neg_hi:[0,1]
	v_cvt_f32_i32_e32 v48, v48
	v_pk_add_f32 v[50:51], v[50:51], v[54:55] neg_lo:[0,1] neg_hi:[0,1]
	v_cmp_neq_f32_e64 s[0:1], s53, v62
	v_add_f32_e32 v51, v58, v51
	v_add_f32_e32 v50, v50, v51
	v_add_f32_e32 v51, v53, v50
	v_mul_f32_e32 v55, v57, v51
	v_mul_f32_e32 v52, v56, v55
	v_sub_f32_e32 v53, v53, v51
	v_add_f32_e32 v60, v59, v55
	v_fma_f32 v54, v55, v56, -v52
	v_add_f32_e32 v58, v50, v53
	v_sub_f32_e32 v50, v60, v59
	v_fmac_f32_e32 v54, v55, v49
	v_sub_f32_e32 v49, v55, v50
	v_add_f32_e32 v50, v52, v54
	v_sub_f32_e32 v53, v51, v50
	v_mov_b32_e32 v55, v50
	v_pk_add_f32 v[50:51], v[50:51], v[52:53] neg_lo:[0,1] neg_hi:[0,1]
	s_nop 0
	v_pk_add_f32 v[50:51], v[50:51], v[54:55] neg_lo:[0,1] neg_hi:[0,1]
	s_nop 0
	v_add_f32_e32 v51, v58, v51
	v_add_f32_e32 v50, v50, v51
	v_add_f32_e32 v50, v53, v50
	v_mul_f32_e32 v50, v57, v50
	v_add_f32_e32 v49, v49, v50
	v_add_f32_e32 v50, v60, v49
	v_mul_f32_e32 v52, v50, v50
	v_sub_f32_e32 v53, v50, v60
	v_fmamk_f32 v54, v52, 0x3e9b6dac, v211
	v_sub_f32_e32 v53, v49, v53
	v_mul_f32_e32 v49, v50, v52
	v_fmaak_f32 v221, v52, v54, 0x3f2aaada
	v_ldexp_f32 v55, v53, 1
	v_pk_mul_f32 v[52:53], v[48:49], v[220:221]
	v_ldexp_f32 v51, v50, 1
	v_fma_f32 v50, v48, s52, -v52
	v_fmac_f32_e32 v50, 0xb102e308, v48
	v_pk_add_f32 v[48:49], v[52:53], v[50:51]
	v_mov_b32_e32 v54, v52
	v_sub_f32_e32 v58, v49, v51
	v_pk_add_f32 v[56:57], v[48:49], v[52:53] neg_lo:[0,1] neg_hi:[0,1]
	v_sub_f32_e32 v52, v53, v58
	v_add_f32_e32 v55, v55, v52
	v_pk_add_f32 v[52:53], v[48:49], v[54:55]
	v_mov_b32_e32 v51, v48
	v_mov_b32_e32 v57, v53
	v_pk_add_f32 v[60:61], v[50:51], v[56:57] neg_lo:[0,1] neg_hi:[0,1]
	v_pk_add_f32 v[50:51], v[50:51], v[56:57]
	v_mov_b32_e32 v59, v48
	v_pk_add_f32 v[56:57], v[50:51], v[48:49] op_sel:[1,0] op_sel_hi:[0,1] neg_lo:[0,1] neg_hi:[0,1]
	v_mov_b32_e32 v58, v55
	v_mov_b32_e32 v54, v53
	v_mov_b32_e32 v55, v51
	v_pk_mov_b32 v[48:49], v[48:49], v[56:57] op_sel:[1,0]
	v_pk_add_f32 v[52:53], v[52:53], v[56:57] op_sel_hi:[1,0] neg_lo:[0,1] neg_hi:[0,1]
	v_pk_add_f32 v[48:49], v[54:55], v[48:49] neg_lo:[0,1] neg_hi:[0,1]
	v_mov_b32_e32 v52, v60
	v_pk_add_f32 v[48:49], v[58:59], v[48:49] neg_lo:[0,1] neg_hi:[0,1]
	v_mov_b32_e32 v61, v51
	v_pk_add_f32 v[52:53], v[52:53], v[48:49]
	s_nop 0
	v_pk_add_f32 v[54:55], v[52:53], v[52:53] op_sel:[0,1] op_sel_hi:[1,0]
	s_nop 0
	v_pk_add_f32 v[50:51], v[50:51], v[54:55] op_sel:[1,0] op_sel_hi:[0,1]
	v_mov_b32_e32 v53, v50
	v_mov_b32_e32 v49, v54
	v_pk_add_f32 v[54:55], v[52:53], v[60:61] neg_lo:[0,1] neg_hi:[0,1]
	s_nop 0
	v_sub_f32_e32 v51, v52, v54
	v_pk_add_f32 v[48:49], v[48:49], v[54:55] neg_lo:[0,1] neg_hi:[0,1]
	v_sub_f32_e32 v51, v60, v51
	v_add_f32_e32 v48, v48, v51
	v_add_f32_e32 v48, v48, v49
	v_add_f32_e32 v48, v50, v48
	v_cndmask_b32_e64 v48, v231, v48, s[0:1]
	v_cmp_ngt_f32_e64 s[0:1], -1.0, v62
	s_nop 1
	v_cndmask_b32_e64 v48, v232, v48, s[0:1]
	v_cmp_neq_f32_e64 s[0:1], -1.0, v62
	s_nop 1
	v_cndmask_b32_e64 v48, v233, v48, s[0:1]
	v_cmp_lt_f32_e64 s[0:1], |v62|, s54
	s_nop 1
	v_cndmask_b32_e64 v48, v48, v62, s[0:1]
	v_sub_f32_e32 v50, v63, v48
	v_lshl_add_u64 v[48:49], v[218:219], 0, s[68:69]
	global_store_dword v[48:49], v50, off
	s_branch .LBB0_112
